# W_in conversion loop pipelined (k=2 instance), conversion units spread over idle and scan WGs
# speedup vs baseline: 1.0341x; 1.0037x over previous
; #define LAS __attribute__((address_space(3)))
; __device__ __forceinline__ bf16_t f2bf(float f) { return (bf16_t)(cvt_pk_bf16(f, 0.f) & 0xffffu); }
; __device__ __forceinline__ float bf2f(bf16_t b) { return __uint_as_float(((unsigned)b) << 16); }
; __device__ __forceinline__ int tidx() { int t = threadIdx.x; asm volatile("" : "+v"(t)); return t; }
; __device__ void conv_unit(LAS unsigned char* lds, const float* src, int ld, int sn0, int nvalid, int k0, int krows,
;                           bf16_t* dst, int dn0, int Kdst, int kd0, const float* gs, const float* bs, float* c1, float* c2) {
;     LAS bf16_t* T = (LAS bf16_t*)lds;
;     LAS float* red = (LAS float*)(lds + 9216);
;     const int tid = tidx(), kl = tid >> 3, ng = (tid & 7) * 8;
;     float a1[8], a2[8], wn[8], gn, bn;
; #pragma unroll
;     for (int j = 0; j < 8; ++j) { a1[j] = 0.f; a2[j] = 0.f; }
;     const int nkt = krows / 64;
;     { const int k = k0 + kl; gn = gs ? gs[k] : 1.f; bn = bs ? bs[k] : 0.f;
; #pragma unroll
;       for (int j = 0; j < 8; ++j) wn[j] = (ng + j < nvalid) ? src[(size_t)k * ld + sn0 + ng + j] : 0.f; }
;     for (int kt = 0; kt < nkt; ++kt) {
;         float w[8]; const float g = gn, b = bn;
; #pragma unroll
;         for (int j = 0; j < 8; ++j) w[j] = wn[j];
;         if (kt + 1 < nkt) { const int k = k0 + (kt + 1) * 64 + kl; gn = gs ? gs[k] : 1.f; bn = bs ? bs[k] : 0.f;
; #pragma unroll
;             for (int j = 0; j < 8; ++j) wn[j] = (ng + j < nvalid) ? src[(size_t)k * ld + sn0 + ng + j] : 0.f; }
; #pragma unroll
;         for (int j = 0; j < 8; ++j) { const bf16_t wb = f2bf(w[j] * g); a1[j] += bf2f(wb); a2[j] += b * w[j]; T[(ng + j) * 72 + kl] = wb; }
.LBB0_535:
	s_load_dwordx2 s[68:69], s[22:23], 0x10
	s_cmp_lg_u64 s[64:65], 0
	s_waitcnt vmcnt(11)
	v_mov_b32_e32 v30, 0
	s_cselect_b64 s[60:61], -1, 0
	s_cmp_eq_u64 s[64:65], 0
	v_mov_b32_e32 v56, 0
	s_cbranch_scc1 .LBB0_537
	v_lshl_add_u64 v[8:9], v[2:3], 2, s[64:65]
	global_load_dword v56, v[8:9], off
.LBB0_537:
	s_mul_i32 s70, s12, 0xc06000
	s_mul_hi_i32 s71, s12, 0xc06000
	s_waitcnt lgkmcnt(0)
	s_add_u32 s14, s68, s70
	s_addc_u32 s15, s69, s71
	v_lshlrev_b32_e32 v0, 3, v27
	v_mov_b64_e32 v[8:9], s[14:15]
	s_movk_i32 s12, 0x3018
	v_and_b32_e32 v17, 56, v0
	v_mad_i64_i32 v[8:9], s[14:15], v2, s12, v[8:9]
	v_lshl_add_u64 v[8:9], s[90:91], 2, v[8:9]
	v_lshlrev_b32_e32 v0, 2, v17
	v_lshl_add_u64 v[10:11], v[8:9], 0, v[0:1]
	v_mov_b32_e32 v8, 0
	v_add_u32_e32 v12, s6, v2
	v_ashrrev_i32_e32 v13, 31, v12
	s_movk_i32 s7, 0x3018
	s_add_u32 s62, s56, 0x2080000
	v_lshlrev_b64 v[12:13], 11, v[12:13]
	v_and_b32_e32 v18, 7, v27
	v_mad_i64_i32 v[10:11], s[14:15], v2, s7, 0
	s_addc_u32 s63, s57, 0
	v_lshl_or_b32 v12, v18, 4, v12
	s_waitcnt vmcnt(2)
	v_lshl_add_u64 v[42:43], s[62:63], 0, v[12:13]
	v_lshlrev_b64 v[12:13], 2, v[2:3]
	s_lshl_b64 s[14:15], s[90:91], 2
	v_lshl_add_u64 v[44:45], s[66:67], 0, v[12:13]
	v_lshl_add_u64 v[46:47], s[64:65], 0, v[12:13]
	v_lshl_add_u64 v[10:11], s[70:71], 0, v[10:11]
	v_lshlrev_b32_e32 v12, 5, v18
	v_mov_b32_e32 v13, v1
	s_add_u32 s14, s68, s14
	v_lshl_add_u64 v[10:11], v[10:11], 0, v[12:13]
	s_addc_u32 s15, s69, s15
	v_lshl_add_u32 v9, v17, 1, 0
	v_lshl_add_u32 v14, v2, 1, 0
	v_mul_lo_u32 v15, v2, s10
	v_mul_u32_u24_e32 v16, 0x90, v17
	v_lshl_add_u64 v[10:11], s[14:15], 0, v[10:11]
	s_mov_b64 s[14:15], 0x10
	s_waitcnt vmcnt(2)
	v_lshl_add_u64 v[50:51], v[10:11], 0, s[14:15]
	s_mov_b64 s[64:65], 0x100
	v_add_u32_e32 v55, v14, v16
	v_add_u32_e32 v3, v9, v15
	v_mov_b32_e32 v9, v8
	v_mov_b32_e32 v10, v8
	v_mov_b32_e32 v11, v8
	v_mov_b32_e32 v12, v8
	v_mov_b32_e32 v13, v8
	v_mov_b32_e32 v14, v8
	v_mov_b32_e32 v15, v8
	v_mov_b32_e32 v48, v8
	v_mov_b32_e32 v49, v8
	v_mov_b32_e32 v40, v8
	v_mov_b32_e32 v41, v8
	v_mov_b32_e32 v38, v8
	v_mov_b32_e32 v39, v8
	v_mov_b32_e32 v34, v8
	v_mov_b32_e32 v35, v8
	v_and_b32_e32 v88, 7, v198
	v_lshl_add_u32 v92, v88, 4, v55
	v_lshrrev_b32_e32 v88, 6, v198
	v_lshl_add_u32 v93, v88, 4, v3
	global_load_dwordx2 v[28:29], v[50:51], off offset:-16
	global_load_dwordx2 v[30:31], v[50:51], off offset:-8
	global_load_dwordx2 v[32:33], v[50:51], off
	global_load_dwordx2 v[36:37], v[50:51], off offset:8
	v_lshl_add_u64 v[50:51], v[50:51], 0, s[2:3]
	global_load_dword v144, v[44:45], off offset:256
	global_load_dword v146, v[46:47], off offset:256
	global_load_dwordx2 v[138:139], v[50:51], off offset:-16
	global_load_dwordx2 v[140:141], v[50:51], off offset:-8
	global_load_dwordx2 v[142:143], v[50:51], off
	global_load_dwordx2 v[148:149], v[50:51], off offset:8
	v_lshl_add_u64 v[50:51], v[50:51], 0, s[2:3]
	global_load_dword v156, v[44:45], off offset:512
	global_load_dword v158, v[46:47], off offset:512
	global_load_dwordx2 v[150:151], v[50:51], off offset:-16
	global_load_dwordx2 v[152:153], v[50:51], off offset:-8
	global_load_dwordx2 v[154:155], v[50:51], off
	global_load_dwordx2 v[160:161], v[50:51], off offset:8
	v_lshl_add_u64 v[50:51], v[50:51], 0, s[2:3]
	global_load_dword v54, v[44:45], off offset:768
	global_load_dword v16, v[46:47], off offset:768
	global_load_dwordx2 v[18:19], v[50:51], off offset:-16
	global_load_dwordx2 v[20:21], v[50:51], off offset:-8
	global_load_dwordx2 v[22:23], v[50:51], off
	global_load_dwordx2 v[24:25], v[50:51], off offset:8
	v_lshl_add_u64 v[50:51], v[50:51], 0, s[2:3]
	s_waitcnt vmcnt(18)
	v_pk_mul_f32 v[162:163], v[28:29], v[26:27] op_sel_hi:[1,0]
	v_cvt_pk_bf16_f32 v164, v162, v163
	v_pk_fma_f32 v[8:9], v[28:29], v[56:57], v[8:9] op_sel_hi:[1,0,1]
	v_lshlrev_b32_e32 v166, 16, v164
	v_and_b32_e32 v167, 0xffff0000, v164
	v_lshrrev_b32_e32 v165, 16, v164
	ds_write_b16 v92, v164
	ds_write_b16 v92, v165 offset:144
	v_pk_add_f32 v[48:49], v[48:49], v[166:167]
	v_pk_mul_f32 v[168:169], v[30:31], v[26:27] op_sel_hi:[1,0]
	v_cvt_pk_bf16_f32 v134, v168, v169
	v_pk_fma_f32 v[10:11], v[30:31], v[56:57], v[10:11] op_sel_hi:[1,0,1]
	v_lshlrev_b32_e32 v58, 16, v134
	v_and_b32_e32 v59, 0xffff0000, v134
	v_lshrrev_b32_e32 v135, 16, v134
	ds_write_b16 v92, v134 offset:288
	ds_write_b16 v92, v135 offset:432
	v_pk_add_f32 v[40:41], v[40:41], v[58:59]
	v_pk_mul_f32 v[162:163], v[32:33], v[26:27] op_sel_hi:[1,0]
	v_cvt_pk_bf16_f32 v164, v162, v163
	v_pk_fma_f32 v[12:13], v[32:33], v[56:57], v[12:13] op_sel_hi:[1,0,1]
	v_lshlrev_b32_e32 v166, 16, v164
	v_and_b32_e32 v167, 0xffff0000, v164
	v_lshrrev_b32_e32 v165, 16, v164
	ds_write_b16 v92, v164 offset:576
	ds_write_b16 v92, v165 offset:720
	v_pk_add_f32 v[38:39], v[38:39], v[166:167]
	v_pk_mul_f32 v[168:169], v[36:37], v[26:27] op_sel_hi:[1,0]
	v_cvt_pk_bf16_f32 v134, v168, v169
	v_pk_fma_f32 v[14:15], v[36:37], v[56:57], v[14:15] op_sel_hi:[1,0,1]
	v_lshlrev_b32_e32 v58, 16, v134
	v_and_b32_e32 v59, 0xffff0000, v134
	v_lshrrev_b32_e32 v135, 16, v134
	ds_write_b16 v92, v134 offset:864
	ds_write_b16 v92, v135 offset:1008
	v_pk_add_f32 v[34:35], v[34:35], v[58:59]
	s_waitcnt lgkmcnt(0)
	s_barrier
; #define LAS __attribute__((address_space(3)))
; __device__ __forceinline__ bf16_t f2bf(float f) { return (bf16_t)(cvt_pk_bf16(f, 0.f) & 0xffffu); }
; __device__ __forceinline__ float bf2f(bf16_t b) { return __uint_as_float(((unsigned)b) << 16); }
; #define LBAR() do { asm volatile("s_waitcnt lgkmcnt(0)" ::: "memory"); __builtin_amdgcn_s_barrier(); asm volatile("" ::: "memory"); } while (0)
; __device__ void conv_unit(LAS unsigned char* lds, const float* src, int ld, int sn0, int nvalid, int k0, int krows,
;                           bf16_t* dst, int dn0, int Kdst, int kd0, const float* gs, const float* bs, float* c1, float* c2) {
;     ...
;     for (int kt = 0; kt < nkt; ++kt) {
;         float w[8]; const float g = gn, b = bn;
; #pragma unroll
;         for (int j = 0; j < 8; ++j) w[j] = wn[j];
;         if (kt + 1 < nkt) { const int k = k0 + (kt + 1) * 64 + kl; gn = gs ? gs[k] : 1.f; bn = bs ? bs[k] : 0.f;
; #pragma unroll
;             for (int j = 0; j < 8; ++j) wn[j] = (ng + j < nvalid) ? src[(size_t)k * ld + sn0 + ng + j] : 0.f; }
; #pragma unroll
;         for (int j = 0; j < 8; ++j) { const bf16_t wb = f2bf(w[j] * g); a1[j] += bf2f(wb); a2[j] += b * w[j]; T[(ng + j) * 72 + kl] = wb; }
;         LBAR();
;         { const int n = tid >> 3, ks = (tid & 7) * 8; const u32x4 v = *(const LAS u32x4*)(T + n * 72 + ks);
;           *(u32x4*)(dst + (size_t)(dn0 + n) * Kdst + kd0 + kt * 64 + ks) = v; }
;         LBAR();
	ds_read_b128 v[88:91], v93
	global_load_dword v26, v[44:45], off offset:1024
	global_load_dword v56, v[46:47], off offset:1024
	global_load_dwordx2 v[28:29], v[50:51], off offset:-16
	global_load_dwordx2 v[30:31], v[50:51], off offset:-8
	global_load_dwordx2 v[32:33], v[50:51], off
	global_load_dwordx2 v[36:37], v[50:51], off offset:8
	v_lshl_add_u64 v[50:51], v[50:51], 0, s[2:3]
	s_waitcnt lgkmcnt(0)
	global_store_dwordx4 v[42:43], v[88:91], off
	s_waitcnt vmcnt(19)
	v_pk_mul_f32 v[162:163], v[138:139], v[144:145] op_sel_hi:[1,0]
	v_cvt_pk_bf16_f32 v164, v162, v163
	v_pk_fma_f32 v[8:9], v[138:139], v[146:147], v[8:9] op_sel_hi:[1,0,1]
	v_lshlrev_b32_e32 v166, 16, v164
	v_and_b32_e32 v167, 0xffff0000, v164
	v_lshrrev_b32_e32 v165, 16, v164
	ds_write_b16 v92, v164 offset:9472
	ds_write_b16 v92, v165 offset:9616
	v_pk_add_f32 v[48:49], v[48:49], v[166:167]
	v_pk_mul_f32 v[168:169], v[140:141], v[144:145] op_sel_hi:[1,0]
	v_cvt_pk_bf16_f32 v134, v168, v169
	v_pk_fma_f32 v[10:11], v[140:141], v[146:147], v[10:11] op_sel_hi:[1,0,1]
	v_lshlrev_b32_e32 v58, 16, v134
	v_and_b32_e32 v59, 0xffff0000, v134
	v_lshrrev_b32_e32 v135, 16, v134
	ds_write_b16 v92, v134 offset:9760
	ds_write_b16 v92, v135 offset:9904
	v_pk_add_f32 v[40:41], v[40:41], v[58:59]
	v_pk_mul_f32 v[162:163], v[142:143], v[144:145] op_sel_hi:[1,0]
	v_cvt_pk_bf16_f32 v164, v162, v163
	v_pk_fma_f32 v[12:13], v[142:143], v[146:147], v[12:13] op_sel_hi:[1,0,1]
	v_lshlrev_b32_e32 v166, 16, v164
	v_and_b32_e32 v167, 0xffff0000, v164
	v_lshrrev_b32_e32 v165, 16, v164
	ds_write_b16 v92, v164 offset:10048
	ds_write_b16 v92, v165 offset:10192
	v_pk_add_f32 v[38:39], v[38:39], v[166:167]
	v_pk_mul_f32 v[168:169], v[148:149], v[144:145] op_sel_hi:[1,0]
	v_cvt_pk_bf16_f32 v134, v168, v169
	v_pk_fma_f32 v[14:15], v[148:149], v[146:147], v[14:15] op_sel_hi:[1,0,1]
	v_lshlrev_b32_e32 v58, 16, v134
	v_and_b32_e32 v59, 0xffff0000, v134
	v_lshrrev_b32_e32 v135, 16, v134
	ds_write_b16 v92, v134 offset:10336
	ds_write_b16 v92, v135 offset:10480
	v_pk_add_f32 v[34:35], v[34:35], v[58:59]
	s_waitcnt lgkmcnt(0)
	s_barrier
	ds_read_b128 v[184:187], v93 offset:9472
	global_load_dword v144, v[44:45], off offset:1280
	global_load_dword v146, v[46:47], off offset:1280
	global_load_dwordx2 v[138:139], v[50:51], off offset:-16
	global_load_dwordx2 v[140:141], v[50:51], off offset:-8
	global_load_dwordx2 v[142:143], v[50:51], off
	global_load_dwordx2 v[148:149], v[50:51], off offset:8
	v_lshl_add_u64 v[50:51], v[50:51], 0, s[2:3]
	s_waitcnt lgkmcnt(0)
	global_store_dwordx4 v[42:43], v[184:187], off offset:128
	s_waitcnt vmcnt(20)
	v_pk_mul_f32 v[162:163], v[150:151], v[156:157] op_sel_hi:[1,0]
	v_cvt_pk_bf16_f32 v164, v162, v163
	v_pk_fma_f32 v[8:9], v[150:151], v[158:159], v[8:9] op_sel_hi:[1,0,1]
	v_lshlrev_b32_e32 v166, 16, v164
	v_and_b32_e32 v167, 0xffff0000, v164
	v_lshrrev_b32_e32 v165, 16, v164
	ds_write_b16 v92, v164
	ds_write_b16 v92, v165 offset:144
	v_pk_add_f32 v[48:49], v[48:49], v[166:167]
	v_pk_mul_f32 v[168:169], v[152:153], v[156:157] op_sel_hi:[1,0]
	v_cvt_pk_bf16_f32 v134, v168, v169
	v_pk_fma_f32 v[10:11], v[152:153], v[158:159], v[10:11] op_sel_hi:[1,0,1]
	v_lshlrev_b32_e32 v58, 16, v134
	v_and_b32_e32 v59, 0xffff0000, v134
	v_lshrrev_b32_e32 v135, 16, v134
	ds_write_b16 v92, v134 offset:288
	ds_write_b16 v92, v135 offset:432
	v_pk_add_f32 v[40:41], v[40:41], v[58:59]
	v_pk_mul_f32 v[162:163], v[154:155], v[156:157] op_sel_hi:[1,0]
	v_cvt_pk_bf16_f32 v164, v162, v163
	v_pk_fma_f32 v[12:13], v[154:155], v[158:159], v[12:13] op_sel_hi:[1,0,1]
	v_lshlrev_b32_e32 v166, 16, v164
	v_and_b32_e32 v167, 0xffff0000, v164
	v_lshrrev_b32_e32 v165, 16, v164
	ds_write_b16 v92, v164 offset:576
	ds_write_b16 v92, v165 offset:720
	v_pk_add_f32 v[38:39], v[38:39], v[166:167]
	v_pk_mul_f32 v[168:169], v[160:161], v[156:157] op_sel_hi:[1,0]
	v_cvt_pk_bf16_f32 v134, v168, v169
	v_pk_fma_f32 v[14:15], v[160:161], v[158:159], v[14:15] op_sel_hi:[1,0,1]
	v_lshlrev_b32_e32 v58, 16, v134
	v_and_b32_e32 v59, 0xffff0000, v134
	v_lshrrev_b32_e32 v135, 16, v134
	ds_write_b16 v92, v134 offset:864
	ds_write_b16 v92, v135 offset:1008
	v_pk_add_f32 v[34:35], v[34:35], v[58:59]
	s_waitcnt lgkmcnt(0)
	s_barrier
	ds_read_b128 v[88:91], v93
	global_load_dword v156, v[44:45], off offset:1536
	global_load_dword v158, v[46:47], off offset:1536
	global_load_dwordx2 v[150:151], v[50:51], off offset:-16
	global_load_dwordx2 v[152:153], v[50:51], off offset:-8
	global_load_dwordx2 v[154:155], v[50:51], off
	global_load_dwordx2 v[160:161], v[50:51], off offset:8
	v_lshl_add_u64 v[50:51], v[50:51], 0, s[2:3]
	s_waitcnt lgkmcnt(0)
	global_store_dwordx4 v[42:43], v[88:91], off offset:256
	s_waitcnt vmcnt(21)
	v_pk_mul_f32 v[162:163], v[18:19], v[54:55] op_sel_hi:[1,0]
	v_cvt_pk_bf16_f32 v164, v162, v163
	v_pk_fma_f32 v[8:9], v[18:19], v[16:17], v[8:9] op_sel_hi:[1,0,1]
	v_lshlrev_b32_e32 v166, 16, v164
	v_and_b32_e32 v167, 0xffff0000, v164
	v_lshrrev_b32_e32 v165, 16, v164
	ds_write_b16 v92, v164 offset:9472
	ds_write_b16 v92, v165 offset:9616
	v_pk_add_f32 v[48:49], v[48:49], v[166:167]
	v_pk_mul_f32 v[168:169], v[20:21], v[54:55] op_sel_hi:[1,0]
	v_cvt_pk_bf16_f32 v134, v168, v169
	v_pk_fma_f32 v[10:11], v[20:21], v[16:17], v[10:11] op_sel_hi:[1,0,1]
	v_lshlrev_b32_e32 v58, 16, v134
	v_and_b32_e32 v59, 0xffff0000, v134
	v_lshrrev_b32_e32 v135, 16, v134
	ds_write_b16 v92, v134 offset:9760
	ds_write_b16 v92, v135 offset:9904
	v_pk_add_f32 v[40:41], v[40:41], v[58:59]
	v_pk_mul_f32 v[162:163], v[22:23], v[54:55] op_sel_hi:[1,0]
	v_cvt_pk_bf16_f32 v164, v162, v163
	v_pk_fma_f32 v[12:13], v[22:23], v[16:17], v[12:13] op_sel_hi:[1,0,1]
	v_lshlrev_b32_e32 v166, 16, v164
	v_and_b32_e32 v167, 0xffff0000, v164
	v_lshrrev_b32_e32 v165, 16, v164
	ds_write_b16 v92, v164 offset:10048
	ds_write_b16 v92, v165 offset:10192
	v_pk_add_f32 v[38:39], v[38:39], v[166:167]
	v_pk_mul_f32 v[168:169], v[24:25], v[54:55] op_sel_hi:[1,0]
	v_cvt_pk_bf16_f32 v134, v168, v169
	v_pk_fma_f32 v[14:15], v[24:25], v[16:17], v[14:15] op_sel_hi:[1,0,1]
	v_lshlrev_b32_e32 v58, 16, v134
	v_and_b32_e32 v59, 0xffff0000, v134
	v_lshrrev_b32_e32 v135, 16, v134
	ds_write_b16 v92, v134 offset:10336
	ds_write_b16 v92, v135 offset:10480
	v_pk_add_f32 v[34:35], v[34:35], v[58:59]
	s_waitcnt lgkmcnt(0)
	s_barrier
; #define LAS __attribute__((address_space(3)))
; __device__ __forceinline__ bf16_t f2bf(float f) { return (bf16_t)(cvt_pk_bf16(f, 0.f) & 0xffffu); }
; __device__ __forceinline__ float bf2f(bf16_t b) { return __uint_as_float(((unsigned)b) << 16); }
; #define LBAR() do { asm volatile("s_waitcnt lgkmcnt(0)" ::: "memory"); __builtin_amdgcn_s_barrier(); asm volatile("" ::: "memory"); } while (0)
; __device__ void conv_unit(LAS unsigned char* lds, const float* src, int ld, int sn0, int nvalid, int k0, int krows,
;                           bf16_t* dst, int dn0, int Kdst, int kd0, const float* gs, const float* bs, float* c1, float* c2) {
;     ...
;     for (int kt = 0; kt < nkt; ++kt) {
;         float w[8]; const float g = gn, b = bn;
; #pragma unroll
;         for (int j = 0; j < 8; ++j) w[j] = wn[j];
;         if (kt + 1 < nkt) { const int k = k0 + (kt + 1) * 64 + kl; gn = gs ? gs[k] : 1.f; bn = bs ? bs[k] : 0.f;
; #pragma unroll
;             for (int j = 0; j < 8; ++j) wn[j] = (ng + j < nvalid) ? src[(size_t)k * ld + sn0 + ng + j] : 0.f; }
; #pragma unroll
;         for (int j = 0; j < 8; ++j) { const bf16_t wb = f2bf(w[j] * g); a1[j] += bf2f(wb); a2[j] += b * w[j]; T[(ng + j) * 72 + kl] = wb; }
;         LBAR();
;         { const int n = tid >> 3, ks = (tid & 7) * 8; const u32x4 v = *(const LAS u32x4*)(T + n * 72 + ks);
;           *(u32x4*)(dst + (size_t)(dn0 + n) * Kdst + kd0 + kt * 64 + ks) = v; }
;         LBAR();
	ds_read_b128 v[184:187], v93 offset:9472
	global_load_dword v54, v[44:45], off offset:1792
	global_load_dword v16, v[46:47], off offset:1792
	global_load_dwordx2 v[18:19], v[50:51], off offset:-16
	global_load_dwordx2 v[20:21], v[50:51], off offset:-8
	global_load_dwordx2 v[22:23], v[50:51], off
	global_load_dwordx2 v[24:25], v[50:51], off offset:8
	v_lshl_add_u64 v[50:51], v[50:51], 0, s[2:3]
	s_waitcnt lgkmcnt(0)
	global_store_dwordx4 v[42:43], v[184:187], off offset:384
	s_waitcnt vmcnt(22)
	v_pk_mul_f32 v[162:163], v[28:29], v[26:27] op_sel_hi:[1,0]
	v_cvt_pk_bf16_f32 v164, v162, v163
	v_pk_fma_f32 v[8:9], v[28:29], v[56:57], v[8:9] op_sel_hi:[1,0,1]
	v_lshlrev_b32_e32 v166, 16, v164
	v_and_b32_e32 v167, 0xffff0000, v164
	v_lshrrev_b32_e32 v165, 16, v164
	ds_write_b16 v92, v164
	ds_write_b16 v92, v165 offset:144
	v_pk_add_f32 v[48:49], v[48:49], v[166:167]
	v_pk_mul_f32 v[168:169], v[30:31], v[26:27] op_sel_hi:[1,0]
	v_cvt_pk_bf16_f32 v134, v168, v169
	v_pk_fma_f32 v[10:11], v[30:31], v[56:57], v[10:11] op_sel_hi:[1,0,1]
	v_lshlrev_b32_e32 v58, 16, v134
	v_and_b32_e32 v59, 0xffff0000, v134
	v_lshrrev_b32_e32 v135, 16, v134
	ds_write_b16 v92, v134 offset:288
	ds_write_b16 v92, v135 offset:432
	v_pk_add_f32 v[40:41], v[40:41], v[58:59]
	v_pk_mul_f32 v[162:163], v[32:33], v[26:27] op_sel_hi:[1,0]
	v_cvt_pk_bf16_f32 v164, v162, v163
	v_pk_fma_f32 v[12:13], v[32:33], v[56:57], v[12:13] op_sel_hi:[1,0,1]
	v_lshlrev_b32_e32 v166, 16, v164
	v_and_b32_e32 v167, 0xffff0000, v164
	v_lshrrev_b32_e32 v165, 16, v164
	ds_write_b16 v92, v164 offset:576
	ds_write_b16 v92, v165 offset:720
	v_pk_add_f32 v[38:39], v[38:39], v[166:167]
	v_pk_mul_f32 v[168:169], v[36:37], v[26:27] op_sel_hi:[1,0]
	v_cvt_pk_bf16_f32 v134, v168, v169
	v_pk_fma_f32 v[14:15], v[36:37], v[56:57], v[14:15] op_sel_hi:[1,0,1]
	v_lshlrev_b32_e32 v58, 16, v134
	v_and_b32_e32 v59, 0xffff0000, v134
	v_lshrrev_b32_e32 v135, 16, v134
	ds_write_b16 v92, v134 offset:864
	ds_write_b16 v92, v135 offset:1008
	v_pk_add_f32 v[34:35], v[34:35], v[58:59]
	s_waitcnt lgkmcnt(0)
	s_barrier
	ds_read_b128 v[88:91], v93
	global_load_dword v26, v[44:45], off offset:2048
	global_load_dword v56, v[46:47], off offset:2048
	global_load_dwordx2 v[28:29], v[50:51], off offset:-16
	global_load_dwordx2 v[30:31], v[50:51], off offset:-8
	global_load_dwordx2 v[32:33], v[50:51], off
	global_load_dwordx2 v[36:37], v[50:51], off offset:8
	v_lshl_add_u64 v[50:51], v[50:51], 0, s[2:3]
	s_waitcnt lgkmcnt(0)
	global_store_dwordx4 v[42:43], v[88:91], off offset:512
	s_waitcnt vmcnt(22)
	v_pk_mul_f32 v[162:163], v[138:139], v[144:145] op_sel_hi:[1,0]
	v_cvt_pk_bf16_f32 v164, v162, v163
	v_pk_fma_f32 v[8:9], v[138:139], v[146:147], v[8:9] op_sel_hi:[1,0,1]
	v_lshlrev_b32_e32 v166, 16, v164
	v_and_b32_e32 v167, 0xffff0000, v164
	v_lshrrev_b32_e32 v165, 16, v164
	ds_write_b16 v92, v164 offset:9472
	ds_write_b16 v92, v165 offset:9616
	v_pk_add_f32 v[48:49], v[48:49], v[166:167]
	v_pk_mul_f32 v[168:169], v[140:141], v[144:145] op_sel_hi:[1,0]
	v_cvt_pk_bf16_f32 v134, v168, v169
	v_pk_fma_f32 v[10:11], v[140:141], v[146:147], v[10:11] op_sel_hi:[1,0,1]
	v_lshlrev_b32_e32 v58, 16, v134
	v_and_b32_e32 v59, 0xffff0000, v134
	v_lshrrev_b32_e32 v135, 16, v134
	ds_write_b16 v92, v134 offset:9760
	ds_write_b16 v92, v135 offset:9904
	v_pk_add_f32 v[40:41], v[40:41], v[58:59]
	v_pk_mul_f32 v[162:163], v[142:143], v[144:145] op_sel_hi:[1,0]
	v_cvt_pk_bf16_f32 v164, v162, v163
	v_pk_fma_f32 v[12:13], v[142:143], v[146:147], v[12:13] op_sel_hi:[1,0,1]
	v_lshlrev_b32_e32 v166, 16, v164
	v_and_b32_e32 v167, 0xffff0000, v164
	v_lshrrev_b32_e32 v165, 16, v164
	ds_write_b16 v92, v164 offset:10048
	ds_write_b16 v92, v165 offset:10192
	v_pk_add_f32 v[38:39], v[38:39], v[166:167]
	v_pk_mul_f32 v[168:169], v[148:149], v[144:145] op_sel_hi:[1,0]
	v_cvt_pk_bf16_f32 v134, v168, v169
	v_pk_fma_f32 v[14:15], v[148:149], v[146:147], v[14:15] op_sel_hi:[1,0,1]
	v_lshlrev_b32_e32 v58, 16, v134
	v_and_b32_e32 v59, 0xffff0000, v134
	v_lshrrev_b32_e32 v135, 16, v134
	ds_write_b16 v92, v134 offset:10336
	ds_write_b16 v92, v135 offset:10480
	v_pk_add_f32 v[34:35], v[34:35], v[58:59]
	s_waitcnt lgkmcnt(0)
	s_barrier
	ds_read_b128 v[184:187], v93 offset:9472
	global_load_dword v144, v[44:45], off offset:2304
	global_load_dword v146, v[46:47], off offset:2304
	global_load_dwordx2 v[138:139], v[50:51], off offset:-16
	global_load_dwordx2 v[140:141], v[50:51], off offset:-8
	global_load_dwordx2 v[142:143], v[50:51], off
	global_load_dwordx2 v[148:149], v[50:51], off offset:8
	v_lshl_add_u64 v[50:51], v[50:51], 0, s[2:3]
	s_waitcnt lgkmcnt(0)
	global_store_dwordx4 v[42:43], v[184:187], off offset:640
	s_waitcnt vmcnt(22)
	v_pk_mul_f32 v[162:163], v[150:151], v[156:157] op_sel_hi:[1,0]
	v_cvt_pk_bf16_f32 v164, v162, v163
	v_pk_fma_f32 v[8:9], v[150:151], v[158:159], v[8:9] op_sel_hi:[1,0,1]
	v_lshlrev_b32_e32 v166, 16, v164
	v_and_b32_e32 v167, 0xffff0000, v164
	v_lshrrev_b32_e32 v165, 16, v164
	ds_write_b16 v92, v164
	ds_write_b16 v92, v165 offset:144
	v_pk_add_f32 v[48:49], v[48:49], v[166:167]
	v_pk_mul_f32 v[168:169], v[152:153], v[156:157] op_sel_hi:[1,0]
	v_cvt_pk_bf16_f32 v134, v168, v169
	v_pk_fma_f32 v[10:11], v[152:153], v[158:159], v[10:11] op_sel_hi:[1,0,1]
	v_lshlrev_b32_e32 v58, 16, v134
	v_and_b32_e32 v59, 0xffff0000, v134
	v_lshrrev_b32_e32 v135, 16, v134
	ds_write_b16 v92, v134 offset:288
	ds_write_b16 v92, v135 offset:432
	v_pk_add_f32 v[40:41], v[40:41], v[58:59]
	v_pk_mul_f32 v[162:163], v[154:155], v[156:157] op_sel_hi:[1,0]
	v_cvt_pk_bf16_f32 v164, v162, v163
	v_pk_fma_f32 v[12:13], v[154:155], v[158:159], v[12:13] op_sel_hi:[1,0,1]
	v_lshlrev_b32_e32 v166, 16, v164
	v_and_b32_e32 v167, 0xffff0000, v164
	v_lshrrev_b32_e32 v165, 16, v164
	ds_write_b16 v92, v164 offset:576
	ds_write_b16 v92, v165 offset:720
	v_pk_add_f32 v[38:39], v[38:39], v[166:167]
	v_pk_mul_f32 v[168:169], v[160:161], v[156:157] op_sel_hi:[1,0]
	v_cvt_pk_bf16_f32 v134, v168, v169
	v_pk_fma_f32 v[14:15], v[160:161], v[158:159], v[14:15] op_sel_hi:[1,0,1]
	v_lshlrev_b32_e32 v58, 16, v134
	v_and_b32_e32 v59, 0xffff0000, v134
	v_lshrrev_b32_e32 v135, 16, v134
	ds_write_b16 v92, v134 offset:864
	ds_write_b16 v92, v135 offset:1008
	v_pk_add_f32 v[34:35], v[34:35], v[58:59]
	s_waitcnt lgkmcnt(0)
	s_barrier
; #define LAS __attribute__((address_space(3)))
; __device__ __forceinline__ bf16_t f2bf(float f) { return (bf16_t)(cvt_pk_bf16(f, 0.f) & 0xffffu); }
; __device__ __forceinline__ float bf2f(bf16_t b) { return __uint_as_float(((unsigned)b) << 16); }
; #define LBAR() do { asm volatile("s_waitcnt lgkmcnt(0)" ::: "memory"); __builtin_amdgcn_s_barrier(); asm volatile("" ::: "memory"); } while (0)
; __device__ void conv_unit(LAS unsigned char* lds, const float* src, int ld, int sn0, int nvalid, int k0, int krows,
;                           bf16_t* dst, int dn0, int Kdst, int kd0, const float* gs, const float* bs, float* c1, float* c2) {
;     ...
;     for (int kt = 0; kt < nkt; ++kt) {
;         float w[8]; const float g = gn, b = bn;
; #pragma unroll
;         for (int j = 0; j < 8; ++j) w[j] = wn[j];
;         if (kt + 1 < nkt) { const int k = k0 + (kt + 1) * 64 + kl; gn = gs ? gs[k] : 1.f; bn = bs ? bs[k] : 0.f;
; #pragma unroll
;             for (int j = 0; j < 8; ++j) wn[j] = (ng + j < nvalid) ? src[(size_t)k * ld + sn0 + ng + j] : 0.f; }
; #pragma unroll
;         for (int j = 0; j < 8; ++j) { const bf16_t wb = f2bf(w[j] * g); a1[j] += bf2f(wb); a2[j] += b * w[j]; T[(ng + j) * 72 + kl] = wb; }
;         LBAR();
;         { const int n = tid >> 3, ks = (tid & 7) * 8; const u32x4 v = *(const LAS u32x4*)(T + n * 72 + ks);
;           *(u32x4*)(dst + (size_t)(dn0 + n) * Kdst + kd0 + kt * 64 + ks) = v; }
;         LBAR();
	ds_read_b128 v[88:91], v93
	global_load_dword v156, v[44:45], off offset:2560
	global_load_dword v158, v[46:47], off offset:2560
	global_load_dwordx2 v[150:151], v[50:51], off offset:-16
	global_load_dwordx2 v[152:153], v[50:51], off offset:-8
	global_load_dwordx2 v[154:155], v[50:51], off
	global_load_dwordx2 v[160:161], v[50:51], off offset:8
	v_lshl_add_u64 v[50:51], v[50:51], 0, s[2:3]
	s_waitcnt lgkmcnt(0)
	global_store_dwordx4 v[42:43], v[88:91], off offset:768
	s_waitcnt vmcnt(22)
	v_pk_mul_f32 v[162:163], v[18:19], v[54:55] op_sel_hi:[1,0]
	v_cvt_pk_bf16_f32 v164, v162, v163
	v_pk_fma_f32 v[8:9], v[18:19], v[16:17], v[8:9] op_sel_hi:[1,0,1]
	v_lshlrev_b32_e32 v166, 16, v164
	v_and_b32_e32 v167, 0xffff0000, v164
	v_lshrrev_b32_e32 v165, 16, v164
	ds_write_b16 v92, v164 offset:9472
	ds_write_b16 v92, v165 offset:9616
	v_pk_add_f32 v[48:49], v[48:49], v[166:167]
	v_pk_mul_f32 v[168:169], v[20:21], v[54:55] op_sel_hi:[1,0]
	v_cvt_pk_bf16_f32 v134, v168, v169
	v_pk_fma_f32 v[10:11], v[20:21], v[16:17], v[10:11] op_sel_hi:[1,0,1]
	v_lshlrev_b32_e32 v58, 16, v134
	v_and_b32_e32 v59, 0xffff0000, v134
	v_lshrrev_b32_e32 v135, 16, v134
	ds_write_b16 v92, v134 offset:9760
	ds_write_b16 v92, v135 offset:9904
	v_pk_add_f32 v[40:41], v[40:41], v[58:59]
	v_pk_mul_f32 v[162:163], v[22:23], v[54:55] op_sel_hi:[1,0]
	v_cvt_pk_bf16_f32 v164, v162, v163
	v_pk_fma_f32 v[12:13], v[22:23], v[16:17], v[12:13] op_sel_hi:[1,0,1]
	v_lshlrev_b32_e32 v166, 16, v164
	v_and_b32_e32 v167, 0xffff0000, v164
	v_lshrrev_b32_e32 v165, 16, v164
	ds_write_b16 v92, v164 offset:10048
	ds_write_b16 v92, v165 offset:10192
	v_pk_add_f32 v[38:39], v[38:39], v[166:167]
	v_pk_mul_f32 v[168:169], v[24:25], v[54:55] op_sel_hi:[1,0]
	v_cvt_pk_bf16_f32 v134, v168, v169
	v_pk_fma_f32 v[14:15], v[24:25], v[16:17], v[14:15] op_sel_hi:[1,0,1]
	v_lshlrev_b32_e32 v58, 16, v134
	v_and_b32_e32 v59, 0xffff0000, v134
	v_lshrrev_b32_e32 v135, 16, v134
	ds_write_b16 v92, v134 offset:10336
	ds_write_b16 v92, v135 offset:10480
	v_pk_add_f32 v[34:35], v[34:35], v[58:59]
	s_waitcnt lgkmcnt(0)
	s_barrier
	ds_read_b128 v[184:187], v93 offset:9472
	global_load_dword v54, v[44:45], off offset:2816
	global_load_dword v16, v[46:47], off offset:2816
	global_load_dwordx2 v[18:19], v[50:51], off offset:-16
	global_load_dwordx2 v[20:21], v[50:51], off offset:-8
	global_load_dwordx2 v[22:23], v[50:51], off
	global_load_dwordx2 v[24:25], v[50:51], off offset:8
	v_lshl_add_u64 v[50:51], v[50:51], 0, s[2:3]
	s_waitcnt lgkmcnt(0)
	global_store_dwordx4 v[42:43], v[184:187], off offset:896
	s_waitcnt vmcnt(22)
	v_pk_mul_f32 v[162:163], v[28:29], v[26:27] op_sel_hi:[1,0]
	v_cvt_pk_bf16_f32 v164, v162, v163
	v_pk_fma_f32 v[8:9], v[28:29], v[56:57], v[8:9] op_sel_hi:[1,0,1]
	v_lshlrev_b32_e32 v166, 16, v164
	v_and_b32_e32 v167, 0xffff0000, v164
	v_lshrrev_b32_e32 v165, 16, v164
	ds_write_b16 v92, v164
	ds_write_b16 v92, v165 offset:144
	v_pk_add_f32 v[48:49], v[48:49], v[166:167]
	v_pk_mul_f32 v[168:169], v[30:31], v[26:27] op_sel_hi:[1,0]
	v_cvt_pk_bf16_f32 v134, v168, v169
	v_pk_fma_f32 v[10:11], v[30:31], v[56:57], v[10:11] op_sel_hi:[1,0,1]
	v_lshlrev_b32_e32 v58, 16, v134
	v_and_b32_e32 v59, 0xffff0000, v134
	v_lshrrev_b32_e32 v135, 16, v134
	ds_write_b16 v92, v134 offset:288
	ds_write_b16 v92, v135 offset:432
	v_pk_add_f32 v[40:41], v[40:41], v[58:59]
	v_pk_mul_f32 v[162:163], v[32:33], v[26:27] op_sel_hi:[1,0]
	v_cvt_pk_bf16_f32 v164, v162, v163
	v_pk_fma_f32 v[12:13], v[32:33], v[56:57], v[12:13] op_sel_hi:[1,0,1]
	v_lshlrev_b32_e32 v166, 16, v164
	v_and_b32_e32 v167, 0xffff0000, v164
	v_lshrrev_b32_e32 v165, 16, v164
	ds_write_b16 v92, v164 offset:576
	ds_write_b16 v92, v165 offset:720
	v_pk_add_f32 v[38:39], v[38:39], v[166:167]
	v_pk_mul_f32 v[168:169], v[36:37], v[26:27] op_sel_hi:[1,0]
	v_cvt_pk_bf16_f32 v134, v168, v169
	v_pk_fma_f32 v[14:15], v[36:37], v[56:57], v[14:15] op_sel_hi:[1,0,1]
	v_lshlrev_b32_e32 v58, 16, v134
	v_and_b32_e32 v59, 0xffff0000, v134
	v_lshrrev_b32_e32 v135, 16, v134
	ds_write_b16 v92, v134 offset:864
	ds_write_b16 v92, v135 offset:1008
	v_pk_add_f32 v[34:35], v[34:35], v[58:59]
	s_waitcnt lgkmcnt(0)
	s_barrier
	ds_read_b128 v[88:91], v93
	global_load_dword v26, v[44:45], off offset:3072
	global_load_dword v56, v[46:47], off offset:3072
	global_load_dwordx2 v[28:29], v[50:51], off offset:-16
	global_load_dwordx2 v[30:31], v[50:51], off offset:-8
	global_load_dwordx2 v[32:33], v[50:51], off
	global_load_dwordx2 v[36:37], v[50:51], off offset:8
	v_lshl_add_u64 v[50:51], v[50:51], 0, s[2:3]
	s_waitcnt lgkmcnt(0)
	global_store_dwordx4 v[42:43], v[88:91], off offset:1024
	s_waitcnt vmcnt(22)
	v_pk_mul_f32 v[162:163], v[138:139], v[144:145] op_sel_hi:[1,0]
	v_cvt_pk_bf16_f32 v164, v162, v163
	v_pk_fma_f32 v[8:9], v[138:139], v[146:147], v[8:9] op_sel_hi:[1,0,1]
	v_lshlrev_b32_e32 v166, 16, v164
	v_and_b32_e32 v167, 0xffff0000, v164
	v_lshrrev_b32_e32 v165, 16, v164
	ds_write_b16 v92, v164 offset:9472
	ds_write_b16 v92, v165 offset:9616
	v_pk_add_f32 v[48:49], v[48:49], v[166:167]
	v_pk_mul_f32 v[168:169], v[140:141], v[144:145] op_sel_hi:[1,0]
	v_cvt_pk_bf16_f32 v134, v168, v169
	v_pk_fma_f32 v[10:11], v[140:141], v[146:147], v[10:11] op_sel_hi:[1,0,1]
	v_lshlrev_b32_e32 v58, 16, v134
	v_and_b32_e32 v59, 0xffff0000, v134
	v_lshrrev_b32_e32 v135, 16, v134
	ds_write_b16 v92, v134 offset:9760
	ds_write_b16 v92, v135 offset:9904
	v_pk_add_f32 v[40:41], v[40:41], v[58:59]
	v_pk_mul_f32 v[162:163], v[142:143], v[144:145] op_sel_hi:[1,0]
	v_cvt_pk_bf16_f32 v164, v162, v163
	v_pk_fma_f32 v[12:13], v[142:143], v[146:147], v[12:13] op_sel_hi:[1,0,1]
	v_lshlrev_b32_e32 v166, 16, v164
	v_and_b32_e32 v167, 0xffff0000, v164
	v_lshrrev_b32_e32 v165, 16, v164
	ds_write_b16 v92, v164 offset:10048
	ds_write_b16 v92, v165 offset:10192
	v_pk_add_f32 v[38:39], v[38:39], v[166:167]
	v_pk_mul_f32 v[168:169], v[148:149], v[144:145] op_sel_hi:[1,0]
	v_cvt_pk_bf16_f32 v134, v168, v169
	v_pk_fma_f32 v[14:15], v[148:149], v[146:147], v[14:15] op_sel_hi:[1,0,1]
	v_lshlrev_b32_e32 v58, 16, v134
	v_and_b32_e32 v59, 0xffff0000, v134
	v_lshrrev_b32_e32 v135, 16, v134
	ds_write_b16 v92, v134 offset:10336
	ds_write_b16 v92, v135 offset:10480
	v_pk_add_f32 v[34:35], v[34:35], v[58:59]
	s_waitcnt lgkmcnt(0)
	s_barrier
; #define LAS __attribute__((address_space(3)))
; __device__ __forceinline__ bf16_t f2bf(float f) { return (bf16_t)(cvt_pk_bf16(f, 0.f) & 0xffffu); }
; __device__ __forceinline__ float bf2f(bf16_t b) { return __uint_as_float(((unsigned)b) << 16); }
; #define LBAR() do { asm volatile("s_waitcnt lgkmcnt(0)" ::: "memory"); __builtin_amdgcn_s_barrier(); asm volatile("" ::: "memory"); } while (0)
; __device__ void conv_unit(LAS unsigned char* lds, const float* src, int ld, int sn0, int nvalid, int k0, int krows,
;                           bf16_t* dst, int dn0, int Kdst, int kd0, const float* gs, const float* bs, float* c1, float* c2) {
;     ...
;     for (int kt = 0; kt < nkt; ++kt) {
;         float w[8]; const float g = gn, b = bn;
; #pragma unroll
;         for (int j = 0; j < 8; ++j) w[j] = wn[j];
;         if (kt + 1 < nkt) { const int k = k0 + (kt + 1) * 64 + kl; gn = gs ? gs[k] : 1.f; bn = bs ? bs[k] : 0.f;
; #pragma unroll
;             for (int j = 0; j < 8; ++j) wn[j] = (ng + j < nvalid) ? src[(size_t)k * ld + sn0 + ng + j] : 0.f; }
; #pragma unroll
;         for (int j = 0; j < 8; ++j) { const bf16_t wb = f2bf(w[j] * g); a1[j] += bf2f(wb); a2[j] += b * w[j]; T[(ng + j) * 72 + kl] = wb; }
;         LBAR();
;         { const int n = tid >> 3, ks = (tid & 7) * 8; const u32x4 v = *(const LAS u32x4*)(T + n * 72 + ks);
;           *(u32x4*)(dst + (size_t)(dn0 + n) * Kdst + kd0 + kt * 64 + ks) = v; }
;         LBAR();
	ds_read_b128 v[184:187], v93 offset:9472
	global_load_dword v144, v[44:45], off offset:3328
	global_load_dword v146, v[46:47], off offset:3328
	global_load_dwordx2 v[138:139], v[50:51], off offset:-16
	global_load_dwordx2 v[140:141], v[50:51], off offset:-8
	global_load_dwordx2 v[142:143], v[50:51], off
	global_load_dwordx2 v[148:149], v[50:51], off offset:8
	v_lshl_add_u64 v[50:51], v[50:51], 0, s[2:3]
	s_waitcnt lgkmcnt(0)
	global_store_dwordx4 v[42:43], v[184:187], off offset:1152
	s_waitcnt vmcnt(22)
	v_pk_mul_f32 v[162:163], v[150:151], v[156:157] op_sel_hi:[1,0]
	v_cvt_pk_bf16_f32 v164, v162, v163
	v_pk_fma_f32 v[8:9], v[150:151], v[158:159], v[8:9] op_sel_hi:[1,0,1]
	v_lshlrev_b32_e32 v166, 16, v164
	v_and_b32_e32 v167, 0xffff0000, v164
	v_lshrrev_b32_e32 v165, 16, v164
	ds_write_b16 v92, v164
	ds_write_b16 v92, v165 offset:144
	v_pk_add_f32 v[48:49], v[48:49], v[166:167]
	v_pk_mul_f32 v[168:169], v[152:153], v[156:157] op_sel_hi:[1,0]
	v_cvt_pk_bf16_f32 v134, v168, v169
	v_pk_fma_f32 v[10:11], v[152:153], v[158:159], v[10:11] op_sel_hi:[1,0,1]
	v_lshlrev_b32_e32 v58, 16, v134
	v_and_b32_e32 v59, 0xffff0000, v134
	v_lshrrev_b32_e32 v135, 16, v134
	ds_write_b16 v92, v134 offset:288
	ds_write_b16 v92, v135 offset:432
	v_pk_add_f32 v[40:41], v[40:41], v[58:59]
	v_pk_mul_f32 v[162:163], v[154:155], v[156:157] op_sel_hi:[1,0]
	v_cvt_pk_bf16_f32 v164, v162, v163
	v_pk_fma_f32 v[12:13], v[154:155], v[158:159], v[12:13] op_sel_hi:[1,0,1]
	v_lshlrev_b32_e32 v166, 16, v164
	v_and_b32_e32 v167, 0xffff0000, v164
	v_lshrrev_b32_e32 v165, 16, v164
	ds_write_b16 v92, v164 offset:576
	ds_write_b16 v92, v165 offset:720
	v_pk_add_f32 v[38:39], v[38:39], v[166:167]
	v_pk_mul_f32 v[168:169], v[160:161], v[156:157] op_sel_hi:[1,0]
	v_cvt_pk_bf16_f32 v134, v168, v169
	v_pk_fma_f32 v[14:15], v[160:161], v[158:159], v[14:15] op_sel_hi:[1,0,1]
	v_lshlrev_b32_e32 v58, 16, v134
	v_and_b32_e32 v59, 0xffff0000, v134
	v_lshrrev_b32_e32 v135, 16, v134
	ds_write_b16 v92, v134 offset:864
	ds_write_b16 v92, v135 offset:1008
	v_pk_add_f32 v[34:35], v[34:35], v[58:59]
	s_waitcnt lgkmcnt(0)
	s_barrier
	ds_read_b128 v[88:91], v93
	global_load_dword v156, v[44:45], off offset:3584
	global_load_dword v158, v[46:47], off offset:3584
	global_load_dwordx2 v[150:151], v[50:51], off offset:-16
	global_load_dwordx2 v[152:153], v[50:51], off offset:-8
	global_load_dwordx2 v[154:155], v[50:51], off
	global_load_dwordx2 v[160:161], v[50:51], off offset:8
	v_lshl_add_u64 v[50:51], v[50:51], 0, s[2:3]
	s_waitcnt lgkmcnt(0)
	global_store_dwordx4 v[42:43], v[88:91], off offset:1280
	s_waitcnt vmcnt(22)
	v_pk_mul_f32 v[162:163], v[18:19], v[54:55] op_sel_hi:[1,0]
	v_cvt_pk_bf16_f32 v164, v162, v163
	v_pk_fma_f32 v[8:9], v[18:19], v[16:17], v[8:9] op_sel_hi:[1,0,1]
	v_lshlrev_b32_e32 v166, 16, v164
	v_and_b32_e32 v167, 0xffff0000, v164
	v_lshrrev_b32_e32 v165, 16, v164
	ds_write_b16 v92, v164 offset:9472
	ds_write_b16 v92, v165 offset:9616
	v_pk_add_f32 v[48:49], v[48:49], v[166:167]
	v_pk_mul_f32 v[168:169], v[20:21], v[54:55] op_sel_hi:[1,0]
	v_cvt_pk_bf16_f32 v134, v168, v169
	v_pk_fma_f32 v[10:11], v[20:21], v[16:17], v[10:11] op_sel_hi:[1,0,1]
	v_lshlrev_b32_e32 v58, 16, v134
	v_and_b32_e32 v59, 0xffff0000, v134
	v_lshrrev_b32_e32 v135, 16, v134
	ds_write_b16 v92, v134 offset:9760
	ds_write_b16 v92, v135 offset:9904
	v_pk_add_f32 v[40:41], v[40:41], v[58:59]
	v_pk_mul_f32 v[162:163], v[22:23], v[54:55] op_sel_hi:[1,0]
	v_cvt_pk_bf16_f32 v164, v162, v163
	v_pk_fma_f32 v[12:13], v[22:23], v[16:17], v[12:13] op_sel_hi:[1,0,1]
	v_lshlrev_b32_e32 v166, 16, v164
	v_and_b32_e32 v167, 0xffff0000, v164
	v_lshrrev_b32_e32 v165, 16, v164
	ds_write_b16 v92, v164 offset:10048
	ds_write_b16 v92, v165 offset:10192
	v_pk_add_f32 v[38:39], v[38:39], v[166:167]
	v_pk_mul_f32 v[168:169], v[24:25], v[54:55] op_sel_hi:[1,0]
	v_cvt_pk_bf16_f32 v134, v168, v169
	v_pk_fma_f32 v[14:15], v[24:25], v[16:17], v[14:15] op_sel_hi:[1,0,1]
	v_lshlrev_b32_e32 v58, 16, v134
	v_and_b32_e32 v59, 0xffff0000, v134
	v_lshrrev_b32_e32 v135, 16, v134
	ds_write_b16 v92, v134 offset:10336
	ds_write_b16 v92, v135 offset:10480
	v_pk_add_f32 v[34:35], v[34:35], v[58:59]
	s_waitcnt lgkmcnt(0)
	s_barrier
; #define LAS __attribute__((address_space(3)))
; __device__ __forceinline__ bf16_t f2bf(float f) { return (bf16_t)(cvt_pk_bf16(f, 0.f) & 0xffffu); }
; __device__ __forceinline__ float bf2f(bf16_t b) { return __uint_as_float(((unsigned)b) << 16); }
; #define LBAR() do { asm volatile("s_waitcnt lgkmcnt(0)" ::: "memory"); __builtin_amdgcn_s_barrier(); asm volatile("" ::: "memory"); } while (0)
; __device__ void conv_unit(LAS unsigned char* lds, const float* src, int ld, int sn0, int nvalid, int k0, int krows,
;                           bf16_t* dst, int dn0, int Kdst, int kd0, const float* gs, const float* bs, float* c1, float* c2) {
;     ...
;     for (int kt = 0; kt < nkt; ++kt) {
;         float w[8]; const float g = gn, b = bn;
; #pragma unroll
;         for (int j = 0; j < 8; ++j) w[j] = wn[j];
;         if (kt + 1 < nkt) { const int k = k0 + (kt + 1) * 64 + kl; gn = gs ? gs[k] : 1.f; bn = bs ? bs[k] : 0.f;
; #pragma unroll
;             for (int j = 0; j < 8; ++j) wn[j] = (ng + j < nvalid) ? src[(size_t)k * ld + sn0 + ng + j] : 0.f; }
; #pragma unroll
;         for (int j = 0; j < 8; ++j) { const bf16_t wb = f2bf(w[j] * g); a1[j] += bf2f(wb); a2[j] += b * w[j]; T[(ng + j) * 72 + kl] = wb; }
;         LBAR();
;         { const int n = tid >> 3, ks = (tid & 7) * 8; const u32x4 v = *(const LAS u32x4*)(T + n * 72 + ks);
;           *(u32x4*)(dst + (size_t)(dn0 + n) * Kdst + kd0 + kt * 64 + ks) = v; }
;         LBAR();
	ds_read_b128 v[184:187], v93 offset:9472
	global_load_dword v54, v[44:45], off offset:3840
	global_load_dword v16, v[46:47], off offset:3840
	global_load_dwordx2 v[18:19], v[50:51], off offset:-16
	global_load_dwordx2 v[20:21], v[50:51], off offset:-8
	global_load_dwordx2 v[22:23], v[50:51], off
	global_load_dwordx2 v[24:25], v[50:51], off offset:8
	v_lshl_add_u64 v[50:51], v[50:51], 0, s[2:3]
	s_waitcnt lgkmcnt(0)
	global_store_dwordx4 v[42:43], v[184:187], off offset:1408
	s_waitcnt vmcnt(22)
	v_pk_mul_f32 v[162:163], v[28:29], v[26:27] op_sel_hi:[1,0]
	v_cvt_pk_bf16_f32 v164, v162, v163
	v_pk_fma_f32 v[8:9], v[28:29], v[56:57], v[8:9] op_sel_hi:[1,0,1]
	v_lshlrev_b32_e32 v166, 16, v164
	v_and_b32_e32 v167, 0xffff0000, v164
	v_lshrrev_b32_e32 v165, 16, v164
	ds_write_b16 v92, v164
	ds_write_b16 v92, v165 offset:144
	v_pk_add_f32 v[48:49], v[48:49], v[166:167]
	v_pk_mul_f32 v[168:169], v[30:31], v[26:27] op_sel_hi:[1,0]
	v_cvt_pk_bf16_f32 v134, v168, v169
	v_pk_fma_f32 v[10:11], v[30:31], v[56:57], v[10:11] op_sel_hi:[1,0,1]
	v_lshlrev_b32_e32 v58, 16, v134
	v_and_b32_e32 v59, 0xffff0000, v134
	v_lshrrev_b32_e32 v135, 16, v134
	ds_write_b16 v92, v134 offset:288
	ds_write_b16 v92, v135 offset:432
	v_pk_add_f32 v[40:41], v[40:41], v[58:59]
	v_pk_mul_f32 v[162:163], v[32:33], v[26:27] op_sel_hi:[1,0]
	v_cvt_pk_bf16_f32 v164, v162, v163
	v_pk_fma_f32 v[12:13], v[32:33], v[56:57], v[12:13] op_sel_hi:[1,0,1]
	v_lshlrev_b32_e32 v166, 16, v164
	v_and_b32_e32 v167, 0xffff0000, v164
	v_lshrrev_b32_e32 v165, 16, v164
	ds_write_b16 v92, v164 offset:576
	ds_write_b16 v92, v165 offset:720
	v_pk_add_f32 v[38:39], v[38:39], v[166:167]
	v_pk_mul_f32 v[168:169], v[36:37], v[26:27] op_sel_hi:[1,0]
	v_cvt_pk_bf16_f32 v134, v168, v169
	v_pk_fma_f32 v[14:15], v[36:37], v[56:57], v[14:15] op_sel_hi:[1,0,1]
	v_lshlrev_b32_e32 v58, 16, v134
	v_and_b32_e32 v59, 0xffff0000, v134
	v_lshrrev_b32_e32 v135, 16, v134
	ds_write_b16 v92, v134 offset:864
	ds_write_b16 v92, v135 offset:1008
	v_pk_add_f32 v[34:35], v[34:35], v[58:59]
	s_waitcnt lgkmcnt(0)
	s_barrier
	ds_read_b128 v[88:91], v93
	s_waitcnt lgkmcnt(0)
	global_store_dwordx4 v[42:43], v[88:91], off offset:1536
	s_waitcnt vmcnt(16)
	v_pk_mul_f32 v[162:163], v[138:139], v[144:145] op_sel_hi:[1,0]
	v_cvt_pk_bf16_f32 v164, v162, v163
	v_pk_fma_f32 v[8:9], v[138:139], v[146:147], v[8:9] op_sel_hi:[1,0,1]
	v_lshlrev_b32_e32 v166, 16, v164
	v_and_b32_e32 v167, 0xffff0000, v164
	v_lshrrev_b32_e32 v165, 16, v164
	ds_write_b16 v92, v164 offset:9472
	ds_write_b16 v92, v165 offset:9616
	v_pk_add_f32 v[48:49], v[48:49], v[166:167]
	v_pk_mul_f32 v[168:169], v[140:141], v[144:145] op_sel_hi:[1,0]
	v_cvt_pk_bf16_f32 v134, v168, v169
	v_pk_fma_f32 v[10:11], v[140:141], v[146:147], v[10:11] op_sel_hi:[1,0,1]
	v_lshlrev_b32_e32 v58, 16, v134
	v_and_b32_e32 v59, 0xffff0000, v134
	v_lshrrev_b32_e32 v135, 16, v134
	ds_write_b16 v92, v134 offset:9760
	ds_write_b16 v92, v135 offset:9904
	v_pk_add_f32 v[40:41], v[40:41], v[58:59]
	v_pk_mul_f32 v[162:163], v[142:143], v[144:145] op_sel_hi:[1,0]
	v_cvt_pk_bf16_f32 v164, v162, v163
	v_pk_fma_f32 v[12:13], v[142:143], v[146:147], v[12:13] op_sel_hi:[1,0,1]
	v_lshlrev_b32_e32 v166, 16, v164
	v_and_b32_e32 v167, 0xffff0000, v164
	v_lshrrev_b32_e32 v165, 16, v164
	ds_write_b16 v92, v164 offset:10048
	ds_write_b16 v92, v165 offset:10192
	v_pk_add_f32 v[38:39], v[38:39], v[166:167]
	v_pk_mul_f32 v[168:169], v[148:149], v[144:145] op_sel_hi:[1,0]
	v_cvt_pk_bf16_f32 v134, v168, v169
	v_pk_fma_f32 v[14:15], v[148:149], v[146:147], v[14:15] op_sel_hi:[1,0,1]
	v_lshlrev_b32_e32 v58, 16, v134
	v_and_b32_e32 v59, 0xffff0000, v134
	v_lshrrev_b32_e32 v135, 16, v134
	ds_write_b16 v92, v134 offset:10336
	ds_write_b16 v92, v135 offset:10480
	v_pk_add_f32 v[34:35], v[34:35], v[58:59]
	s_waitcnt lgkmcnt(0)
	s_barrier
	ds_read_b128 v[184:187], v93 offset:9472
	s_waitcnt lgkmcnt(0)
	global_store_dwordx4 v[42:43], v[184:187], off offset:1664
	s_waitcnt vmcnt(10)
	v_pk_mul_f32 v[162:163], v[150:151], v[156:157] op_sel_hi:[1,0]
	v_cvt_pk_bf16_f32 v164, v162, v163
	v_pk_fma_f32 v[8:9], v[150:151], v[158:159], v[8:9] op_sel_hi:[1,0,1]
	v_lshlrev_b32_e32 v166, 16, v164
	v_and_b32_e32 v167, 0xffff0000, v164
	v_lshrrev_b32_e32 v165, 16, v164
	ds_write_b16 v92, v164
	ds_write_b16 v92, v165 offset:144
	v_pk_add_f32 v[48:49], v[48:49], v[166:167]
	v_pk_mul_f32 v[168:169], v[152:153], v[156:157] op_sel_hi:[1,0]
	v_cvt_pk_bf16_f32 v134, v168, v169
	v_pk_fma_f32 v[10:11], v[152:153], v[158:159], v[10:11] op_sel_hi:[1,0,1]
	v_lshlrev_b32_e32 v58, 16, v134
	v_and_b32_e32 v59, 0xffff0000, v134
	v_lshrrev_b32_e32 v135, 16, v134
	ds_write_b16 v92, v134 offset:288
	ds_write_b16 v92, v135 offset:432
	v_pk_add_f32 v[40:41], v[40:41], v[58:59]
	v_pk_mul_f32 v[162:163], v[154:155], v[156:157] op_sel_hi:[1,0]
	v_cvt_pk_bf16_f32 v164, v162, v163
	v_pk_fma_f32 v[12:13], v[154:155], v[158:159], v[12:13] op_sel_hi:[1,0,1]
	v_lshlrev_b32_e32 v166, 16, v164
	v_and_b32_e32 v167, 0xffff0000, v164
	v_lshrrev_b32_e32 v165, 16, v164
	ds_write_b16 v92, v164 offset:576
	ds_write_b16 v92, v165 offset:720
	v_pk_add_f32 v[38:39], v[38:39], v[166:167]
	v_pk_mul_f32 v[168:169], v[160:161], v[156:157] op_sel_hi:[1,0]
	v_cvt_pk_bf16_f32 v134, v168, v169
	v_pk_fma_f32 v[14:15], v[160:161], v[158:159], v[14:15] op_sel_hi:[1,0,1]
	v_lshlrev_b32_e32 v58, 16, v134
	v_and_b32_e32 v59, 0xffff0000, v134
	v_lshrrev_b32_e32 v135, 16, v134
	ds_write_b16 v92, v134 offset:864
	ds_write_b16 v92, v135 offset:1008
	v_pk_add_f32 v[34:35], v[34:35], v[58:59]
	s_waitcnt lgkmcnt(0)
	s_barrier
	ds_read_b128 v[88:91], v93
	s_waitcnt lgkmcnt(0)
	global_store_dwordx4 v[42:43], v[88:91], off offset:1792
	s_barrier

; #define LAS __attribute__((address_space(3)))
; __device__ void weights_units(LAS unsigned char* lds, KP& P0, int lm0, int li0, int ufirst, int ustride) {
;     const int n_m = lm0 >= 0 ? 144 : 0, n_i = li0 >= 0 ? 49 : 0, NU = n_m + n_i;
;     for (int u = ufirst; u < NU; u += ustride) {
;         KPtr P_ = P0; int lm = __builtin_amdgcn_readfirstlane(lm0), li = __builtin_amdgcn_readfirstlane(li0); asm volatile("" : "+s"(P_.q), "+s"(lm), "+s"(li));
;         unsigned char* ob = (unsigned char*)p.out; unsigned char* ws = p.ws;
;         if (u < n_m) {
;             if (u < 64) { const float* w1 = p.in[24] + (size_t)lm * DM * DFF;
.LBB0_596:
	v_readlane_b32 s53, v255, 21
	s_nop 1
	s_sub_i32 s53, s53, 153
	s_cmp_ge_i32 s53, 0
	s_cbranch_scc1 .Lk2_conv_go
	s_addk_i32 s53, 0x100
	s_cmpk_gt_i32 s53, 0x8f
	s_cbranch_scc1 .Lk2_conv_done
.Lk2_conv_go:
	s_movk_i32 s13, 0x90
	s_movk_i32 s56, 0x1000
	s_mov_b32 s52, 0x40000
	s_lshl_b32 s6, s53, 6
	s_add_i32 s18, s6, 0xffffe000
	s_branch .LBB0_805
